# ssm_prep Kc table on f32 MFMA (v_mfma_f32_16x16x4_f32) + attention epilogue stores staged through LDS as full-row dwordx4, on top of kept GEMM loop/epilogue edits
# speedup vs baseline: 1.0120x; 1.0103x over previous
.LBB0_76:
	s_or_b64 exec, exec, s[0:1]
	v_readlane_b32 s8, v230, 7
	v_mul_u32_u24_e32 v1, 0x41, v26
	v_lshlrev_b32_e32 v32, 5, v26
	v_readlane_b32 s9, v230, 8
	v_readlane_b32 s10, v230, 9
	s_lshl_b32 s7, s90, 4
	v_lshlrev_b32_e32 v2, 4, v26
	v_lshl_add_u64 v[4:5], s[8:9], 0, v[32:33]
	v_lshlrev_b32_e32 v1, 2, v1
	s_mov_b32 s10, 0
	s_mov_b64 s[4:5], -1
	s_waitcnt lgkmcnt(0)
	s_barrier
	v_readlane_b32 s11, v230, 10
	v_readlane_b32 s12, v230, 11
	v_readlane_b32 s13, v230, 12
	v_readlane_b32 s14, v230, 13
	v_readlane_b32 s15, v230, 14
	v_and_b32_e32 v132, 63, v0
	v_lshrrev_b32_e32 v133, 6, v0
	v_and_b32_e32 v134, 15, v132
	v_lshrrev_b32_e32 v135, 4, v132
	v_lshlrev_b32_e32 v136, 6, v135
	v_lshl_add_u32 v136, v134, 2, v136
	v_add_u32_e32 v136, 0x8408, v136
	ds_read_b32 v100, v136 offset:0
	ds_read_b32 v101, v136 offset:256
	ds_read_b32 v102, v136 offset:512
	ds_read_b32 v103, v136 offset:768
	ds_read_b32 v104, v136 offset:1024
	ds_read_b32 v105, v136 offset:1280
	ds_read_b32 v106, v136 offset:1536
	ds_read_b32 v107, v136 offset:1792
	ds_read_b32 v108, v136 offset:2048
	ds_read_b32 v109, v136 offset:2304
	ds_read_b32 v110, v136 offset:2560
	ds_read_b32 v111, v136 offset:2816
	ds_read_b32 v112, v136 offset:3072
	ds_read_b32 v113, v136 offset:3328
	ds_read_b32 v114, v136 offset:3584
	ds_read_b32 v115, v136 offset:3840
	s_waitcnt lgkmcnt(0)
	ds_read_b32 v116, v136 offset:4096
	ds_read_b32 v117, v136 offset:4352
	ds_read_b32 v118, v136 offset:4608
	ds_read_b32 v119, v136 offset:4864
	ds_read_b32 v120, v136 offset:5120
	ds_read_b32 v121, v136 offset:5376
	ds_read_b32 v122, v136 offset:5632
	ds_read_b32 v123, v136 offset:5888
	ds_read_b32 v124, v136 offset:6144
	ds_read_b32 v125, v136 offset:6400
	ds_read_b32 v126, v136 offset:6656
	ds_read_b32 v127, v136 offset:6912
	ds_read_b32 v128, v136 offset:7168
	ds_read_b32 v129, v136 offset:7424
	ds_read_b32 v130, v136 offset:7680
	ds_read_b32 v131, v136 offset:7936
	v_mul_u32_u24_e32 v137, 0x104, v133
	v_lshl_add_u32 v137, v135, 2, v137
	v_add_u32_e32 v137, 0xa408, v137
	v_mul_u32_u24_e32 v138, 0x104, v134
	v_lshl_add_u32 v138, v135, 2, v138
	v_readlane_b32 s8, v230, 7
	v_readlane_b32 s9, v230, 8
	v_add_u32_e32 v139, s7, v133
	v_lshlrev_b32_e32 v139, 11, v139
	v_lshl_add_u32 v139, v134, 5, v139
	v_lshl_add_u32 v140, v135, 3, v139
	v_mov_b32_e32 v141, 0
	v_lshl_add_u64 v[140:141], v[140:141], 0, s[8:9]
	s_waitcnt lgkmcnt(0)
	v_mov_b32_e32 v144, 0
	v_mov_b32_e32 v145, 0
	v_mov_b32_e32 v146, 0
	v_mov_b32_e32 v147, 0
	v_mov_b32_e32 v148, 0
	v_mov_b32_e32 v149, 0
	v_mov_b32_e32 v150, 0
	v_mov_b32_e32 v151, 0
	ds_read_b32 v152, v137 offset:0
	ds_read_b32 v153, v137 offset:4160
	ds_read_b32 v154, v138 offset:0
	ds_read_b32 v155, v138 offset:16900
	ds_read_b32 v156, v138 offset:4160
	ds_read_b32 v157, v138 offset:21060
	ds_read_b32 v158, v137 offset:16
	ds_read_b32 v159, v137 offset:4176
	ds_read_b32 v160, v138 offset:16
	ds_read_b32 v161, v138 offset:16916
	ds_read_b32 v162, v138 offset:4176
	ds_read_b32 v163, v138 offset:21076
	s_waitcnt lgkmcnt(6)
	v_mul_f32_e32 v172, v153, v155
	v_mul_f32_e32 v173, v152, v155
	v_fma_f32 v164, v152, v154, -v172
	v_fma_f32 v165, -v153, v154, -v173
	v_mul_f32_e32 v172, v153, v157
	v_mul_f32_e32 v173, v152, v157
	v_fma_f32 v166, v152, v156, -v172
	v_fma_f32 v167, -v153, v156, -v173
	s_nop 1
	v_mfma_f32_16x16x4_f32 v[144:147], v100, v164, v[144:147]
	v_mfma_f32_16x16x4_f32 v[148:151], v100, v166, v[148:151]
	v_mfma_f32_16x16x4_f32 v[144:147], v116, v165, v[144:147]
	v_mfma_f32_16x16x4_f32 v[148:151], v116, v167, v[148:151]
	ds_read_b32 v152, v137 offset:32
	ds_read_b32 v153, v137 offset:4192
	ds_read_b32 v154, v138 offset:32
	ds_read_b32 v155, v138 offset:16932
	ds_read_b32 v156, v138 offset:4192
	ds_read_b32 v157, v138 offset:21092
	s_waitcnt lgkmcnt(6)
	v_mul_f32_e32 v172, v159, v161
	v_mul_f32_e32 v173, v158, v161
	v_fma_f32 v168, v158, v160, -v172
	v_fma_f32 v169, -v159, v160, -v173
	v_mul_f32_e32 v172, v159, v163
	v_mul_f32_e32 v173, v158, v163
	v_fma_f32 v170, v158, v162, -v172
	v_fma_f32 v171, -v159, v162, -v173
	s_nop 1
	v_mfma_f32_16x16x4_f32 v[144:147], v101, v168, v[144:147]
	v_mfma_f32_16x16x4_f32 v[148:151], v101, v170, v[148:151]
	v_mfma_f32_16x16x4_f32 v[144:147], v117, v169, v[144:147]
	v_mfma_f32_16x16x4_f32 v[148:151], v117, v171, v[148:151]
	ds_read_b32 v158, v137 offset:48
	ds_read_b32 v159, v137 offset:4208
	ds_read_b32 v160, v138 offset:48
	ds_read_b32 v161, v138 offset:16948
	ds_read_b32 v162, v138 offset:4208
	ds_read_b32 v163, v138 offset:21108
	s_waitcnt lgkmcnt(6)
	v_mul_f32_e32 v172, v153, v155
	v_mul_f32_e32 v173, v152, v155
	v_fma_f32 v164, v152, v154, -v172
	v_fma_f32 v165, -v153, v154, -v173
	v_mul_f32_e32 v172, v153, v157
	v_mul_f32_e32 v173, v152, v157
	v_fma_f32 v166, v152, v156, -v172
	v_fma_f32 v167, -v153, v156, -v173
	s_nop 1
	v_mfma_f32_16x16x4_f32 v[144:147], v102, v164, v[144:147]
	v_mfma_f32_16x16x4_f32 v[148:151], v102, v166, v[148:151]
	v_mfma_f32_16x16x4_f32 v[144:147], v118, v165, v[144:147]
	v_mfma_f32_16x16x4_f32 v[148:151], v118, v167, v[148:151]
	ds_read_b32 v152, v137 offset:64
	ds_read_b32 v153, v137 offset:4224
	ds_read_b32 v154, v138 offset:64
	ds_read_b32 v155, v138 offset:16964
	ds_read_b32 v156, v138 offset:4224
	ds_read_b32 v157, v138 offset:21124
	s_waitcnt lgkmcnt(6)
	v_mul_f32_e32 v172, v159, v161
	v_mul_f32_e32 v173, v158, v161
	v_fma_f32 v168, v158, v160, -v172
	v_fma_f32 v169, -v159, v160, -v173
	v_mul_f32_e32 v172, v159, v163
	v_mul_f32_e32 v173, v158, v163
	v_fma_f32 v170, v158, v162, -v172
	v_fma_f32 v171, -v159, v162, -v173
	s_nop 1
	v_mfma_f32_16x16x4_f32 v[144:147], v103, v168, v[144:147]
	v_mfma_f32_16x16x4_f32 v[148:151], v103, v170, v[148:151]
	v_mfma_f32_16x16x4_f32 v[144:147], v119, v169, v[144:147]
	v_mfma_f32_16x16x4_f32 v[148:151], v119, v171, v[148:151]
	ds_read_b32 v158, v137 offset:80
	ds_read_b32 v159, v137 offset:4240
	ds_read_b32 v160, v138 offset:80
	ds_read_b32 v161, v138 offset:16980
	ds_read_b32 v162, v138 offset:4240
	ds_read_b32 v163, v138 offset:21140
	s_waitcnt lgkmcnt(6)
	v_mul_f32_e32 v172, v153, v155
	v_mul_f32_e32 v173, v152, v155
	v_fma_f32 v164, v152, v154, -v172
	v_fma_f32 v165, -v153, v154, -v173
	v_mul_f32_e32 v172, v153, v157
	v_mul_f32_e32 v173, v152, v157
	v_fma_f32 v166, v152, v156, -v172
	v_fma_f32 v167, -v153, v156, -v173
	s_nop 1
	v_mfma_f32_16x16x4_f32 v[144:147], v104, v164, v[144:147]
	v_mfma_f32_16x16x4_f32 v[148:151], v104, v166, v[148:151]
	v_mfma_f32_16x16x4_f32 v[144:147], v120, v165, v[144:147]
	v_mfma_f32_16x16x4_f32 v[148:151], v120, v167, v[148:151]
	ds_read_b32 v152, v137 offset:96
	ds_read_b32 v153, v137 offset:4256
	ds_read_b32 v154, v138 offset:96
	ds_read_b32 v155, v138 offset:16996
	ds_read_b32 v156, v138 offset:4256
	ds_read_b32 v157, v138 offset:21156
	s_waitcnt lgkmcnt(6)
	v_mul_f32_e32 v172, v159, v161
	v_mul_f32_e32 v173, v158, v161
	v_fma_f32 v168, v158, v160, -v172
	v_fma_f32 v169, -v159, v160, -v173
	v_mul_f32_e32 v172, v159, v163
	v_mul_f32_e32 v173, v158, v163
	v_fma_f32 v170, v158, v162, -v172
	v_fma_f32 v171, -v159, v162, -v173
	s_nop 1
	v_mfma_f32_16x16x4_f32 v[144:147], v105, v168, v[144:147]
	v_mfma_f32_16x16x4_f32 v[148:151], v105, v170, v[148:151]
	v_mfma_f32_16x16x4_f32 v[144:147], v121, v169, v[144:147]
	v_mfma_f32_16x16x4_f32 v[148:151], v121, v171, v[148:151]
	ds_read_b32 v158, v137 offset:112
	ds_read_b32 v159, v137 offset:4272
	ds_read_b32 v160, v138 offset:112
	ds_read_b32 v161, v138 offset:17012
	ds_read_b32 v162, v138 offset:4272
	ds_read_b32 v163, v138 offset:21172
	s_waitcnt lgkmcnt(6)
	v_mul_f32_e32 v172, v153, v155
	v_mul_f32_e32 v173, v152, v155
	v_fma_f32 v164, v152, v154, -v172
	v_fma_f32 v165, -v153, v154, -v173
	v_mul_f32_e32 v172, v153, v157
	v_mul_f32_e32 v173, v152, v157
	v_fma_f32 v166, v152, v156, -v172
	v_fma_f32 v167, -v153, v156, -v173
	s_nop 1
	v_mfma_f32_16x16x4_f32 v[144:147], v106, v164, v[144:147]
	v_mfma_f32_16x16x4_f32 v[148:151], v106, v166, v[148:151]
	v_mfma_f32_16x16x4_f32 v[144:147], v122, v165, v[144:147]
	v_mfma_f32_16x16x4_f32 v[148:151], v122, v167, v[148:151]
	ds_read_b32 v152, v137 offset:128
	ds_read_b32 v153, v137 offset:4288
	ds_read_b32 v154, v138 offset:128
	ds_read_b32 v155, v138 offset:17028
	ds_read_b32 v156, v138 offset:4288
	ds_read_b32 v157, v138 offset:21188
	s_waitcnt lgkmcnt(6)
	v_mul_f32_e32 v172, v159, v161
	v_mul_f32_e32 v173, v158, v161
	v_fma_f32 v168, v158, v160, -v172
	v_fma_f32 v169, -v159, v160, -v173
	v_mul_f32_e32 v172, v159, v163
	v_mul_f32_e32 v173, v158, v163
	v_fma_f32 v170, v158, v162, -v172
	v_fma_f32 v171, -v159, v162, -v173
	s_nop 1
	v_mfma_f32_16x16x4_f32 v[144:147], v107, v168, v[144:147]
	v_mfma_f32_16x16x4_f32 v[148:151], v107, v170, v[148:151]
	v_mfma_f32_16x16x4_f32 v[144:147], v123, v169, v[144:147]
	v_mfma_f32_16x16x4_f32 v[148:151], v123, v171, v[148:151]
	ds_read_b32 v158, v137 offset:144
	ds_read_b32 v159, v137 offset:4304
	ds_read_b32 v160, v138 offset:144
	ds_read_b32 v161, v138 offset:17044
	ds_read_b32 v162, v138 offset:4304
	ds_read_b32 v163, v138 offset:21204
	s_waitcnt lgkmcnt(6)
	v_mul_f32_e32 v172, v153, v155
	v_mul_f32_e32 v173, v152, v155
	v_fma_f32 v164, v152, v154, -v172
	v_fma_f32 v165, -v153, v154, -v173
	v_mul_f32_e32 v172, v153, v157
	v_mul_f32_e32 v173, v152, v157
	v_fma_f32 v166, v152, v156, -v172
	v_fma_f32 v167, -v153, v156, -v173
	s_nop 1
	v_mfma_f32_16x16x4_f32 v[144:147], v108, v164, v[144:147]
	v_mfma_f32_16x16x4_f32 v[148:151], v108, v166, v[148:151]
	v_mfma_f32_16x16x4_f32 v[144:147], v124, v165, v[144:147]
	v_mfma_f32_16x16x4_f32 v[148:151], v124, v167, v[148:151]
	ds_read_b32 v152, v137 offset:160
	ds_read_b32 v153, v137 offset:4320
	ds_read_b32 v154, v138 offset:160
	ds_read_b32 v155, v138 offset:17060
	ds_read_b32 v156, v138 offset:4320
	ds_read_b32 v157, v138 offset:21220
	s_waitcnt lgkmcnt(6)
	v_mul_f32_e32 v172, v159, v161
	v_mul_f32_e32 v173, v158, v161
	v_fma_f32 v168, v158, v160, -v172
	v_fma_f32 v169, -v159, v160, -v173
	v_mul_f32_e32 v172, v159, v163
	v_mul_f32_e32 v173, v158, v163
	v_fma_f32 v170, v158, v162, -v172
	v_fma_f32 v171, -v159, v162, -v173
	s_nop 1
	v_mfma_f32_16x16x4_f32 v[144:147], v109, v168, v[144:147]
	v_mfma_f32_16x16x4_f32 v[148:151], v109, v170, v[148:151]
	v_mfma_f32_16x16x4_f32 v[144:147], v125, v169, v[144:147]
	v_mfma_f32_16x16x4_f32 v[148:151], v125, v171, v[148:151]
	ds_read_b32 v158, v137 offset:176
	ds_read_b32 v159, v137 offset:4336
	ds_read_b32 v160, v138 offset:176
	ds_read_b32 v161, v138 offset:17076
	ds_read_b32 v162, v138 offset:4336
	ds_read_b32 v163, v138 offset:21236
	s_waitcnt lgkmcnt(6)
	v_mul_f32_e32 v172, v153, v155
	v_mul_f32_e32 v173, v152, v155
	v_fma_f32 v164, v152, v154, -v172
	v_fma_f32 v165, -v153, v154, -v173
	v_mul_f32_e32 v172, v153, v157
	v_mul_f32_e32 v173, v152, v157
	v_fma_f32 v166, v152, v156, -v172
	v_fma_f32 v167, -v153, v156, -v173
	s_nop 1
	v_mfma_f32_16x16x4_f32 v[144:147], v110, v164, v[144:147]
	v_mfma_f32_16x16x4_f32 v[148:151], v110, v166, v[148:151]
	v_mfma_f32_16x16x4_f32 v[144:147], v126, v165, v[144:147]
	v_mfma_f32_16x16x4_f32 v[148:151], v126, v167, v[148:151]
	ds_read_b32 v152, v137 offset:192
	ds_read_b32 v153, v137 offset:4352
	ds_read_b32 v154, v138 offset:192
	ds_read_b32 v155, v138 offset:17092
	ds_read_b32 v156, v138 offset:4352
	ds_read_b32 v157, v138 offset:21252
	s_waitcnt lgkmcnt(6)
	v_mul_f32_e32 v172, v159, v161
	v_mul_f32_e32 v173, v158, v161
	v_fma_f32 v168, v158, v160, -v172
	v_fma_f32 v169, -v159, v160, -v173
	v_mul_f32_e32 v172, v159, v163
	v_mul_f32_e32 v173, v158, v163
	v_fma_f32 v170, v158, v162, -v172
	v_fma_f32 v171, -v159, v162, -v173
	s_nop 1
	v_mfma_f32_16x16x4_f32 v[144:147], v111, v168, v[144:147]
	v_mfma_f32_16x16x4_f32 v[148:151], v111, v170, v[148:151]
	v_mfma_f32_16x16x4_f32 v[144:147], v127, v169, v[144:147]
	v_mfma_f32_16x16x4_f32 v[148:151], v127, v171, v[148:151]
	ds_read_b32 v158, v137 offset:208
	ds_read_b32 v159, v137 offset:4368
	ds_read_b32 v160, v138 offset:208
	ds_read_b32 v161, v138 offset:17108
	ds_read_b32 v162, v138 offset:4368
	ds_read_b32 v163, v138 offset:21268
	s_waitcnt lgkmcnt(6)
	v_mul_f32_e32 v172, v153, v155
	v_mul_f32_e32 v173, v152, v155
	v_fma_f32 v164, v152, v154, -v172
	v_fma_f32 v165, -v153, v154, -v173
	v_mul_f32_e32 v172, v153, v157
	v_mul_f32_e32 v173, v152, v157
	v_fma_f32 v166, v152, v156, -v172
	v_fma_f32 v167, -v153, v156, -v173
	s_nop 1
	v_mfma_f32_16x16x4_f32 v[144:147], v112, v164, v[144:147]
	v_mfma_f32_16x16x4_f32 v[148:151], v112, v166, v[148:151]
	v_mfma_f32_16x16x4_f32 v[144:147], v128, v165, v[144:147]
	v_mfma_f32_16x16x4_f32 v[148:151], v128, v167, v[148:151]
	ds_read_b32 v152, v137 offset:224
	ds_read_b32 v153, v137 offset:4384
	ds_read_b32 v154, v138 offset:224
	ds_read_b32 v155, v138 offset:17124
	ds_read_b32 v156, v138 offset:4384
	ds_read_b32 v157, v138 offset:21284
	s_waitcnt lgkmcnt(6)
	v_mul_f32_e32 v172, v159, v161
	v_mul_f32_e32 v173, v158, v161
	v_fma_f32 v168, v158, v160, -v172
	v_fma_f32 v169, -v159, v160, -v173
	v_mul_f32_e32 v172, v159, v163
	v_mul_f32_e32 v173, v158, v163
	v_fma_f32 v170, v158, v162, -v172
	v_fma_f32 v171, -v159, v162, -v173
	s_nop 1
	v_mfma_f32_16x16x4_f32 v[144:147], v113, v168, v[144:147]
	v_mfma_f32_16x16x4_f32 v[148:151], v113, v170, v[148:151]
	v_mfma_f32_16x16x4_f32 v[144:147], v129, v169, v[144:147]
	v_mfma_f32_16x16x4_f32 v[148:151], v129, v171, v[148:151]
	ds_read_b32 v158, v137 offset:240
	ds_read_b32 v159, v137 offset:4400
	ds_read_b32 v160, v138 offset:240
	ds_read_b32 v161, v138 offset:17140
	ds_read_b32 v162, v138 offset:4400
	ds_read_b32 v163, v138 offset:21300
	s_waitcnt lgkmcnt(6)
	v_mul_f32_e32 v172, v153, v155
	v_mul_f32_e32 v173, v152, v155
	v_fma_f32 v164, v152, v154, -v172
	v_fma_f32 v165, -v153, v154, -v173
	v_mul_f32_e32 v172, v153, v157
	v_mul_f32_e32 v173, v152, v157
	v_fma_f32 v166, v152, v156, -v172
	v_fma_f32 v167, -v153, v156, -v173
	s_nop 1
	v_mfma_f32_16x16x4_f32 v[144:147], v114, v164, v[144:147]
	v_mfma_f32_16x16x4_f32 v[148:151], v114, v166, v[148:151]
	v_mfma_f32_16x16x4_f32 v[144:147], v130, v165, v[144:147]
	v_mfma_f32_16x16x4_f32 v[148:151], v130, v167, v[148:151]
	s_waitcnt lgkmcnt(0)
	v_mul_f32_e32 v172, v159, v161
	v_mul_f32_e32 v173, v158, v161
	v_fma_f32 v168, v158, v160, -v172
	v_fma_f32 v169, -v159, v160, -v173
	v_mul_f32_e32 v172, v159, v163
	v_mul_f32_e32 v173, v158, v163
	v_fma_f32 v170, v158, v162, -v172
	v_fma_f32 v171, -v159, v162, -v173
	s_nop 1
	v_mfma_f32_16x16x4_f32 v[144:147], v115, v168, v[144:147]
	v_mfma_f32_16x16x4_f32 v[148:151], v115, v170, v[148:151]
	v_mfma_f32_16x16x4_f32 v[144:147], v131, v169, v[144:147]
	v_mfma_f32_16x16x4_f32 v[148:151], v131, v171, v[148:151]
	v_add_u32_e32 v138, 0x2080, v138
	s_nop 9
	v_cvt_pk_bf16_f32 v174, v144, v145
	v_cvt_pk_bf16_f32 v175, v146, v147
	v_cvt_pk_bf16_f32 v176, v148, v149
	v_cvt_pk_bf16_f32 v177, v150, v151
	global_store_dwordx2 v[140:141], v[174:175], off
	global_store_dwordx2 v[140:141], v[176:177], off offset:512
	v_add_co_u32_e32 v140, vcc, 0x400, v140
	s_nop 1
	v_addc_co_u32_e32 v141, vcc, 0, v141, vcc
	v_mov_b32_e32 v144, 0
	v_mov_b32_e32 v145, 0
	v_mov_b32_e32 v146, 0
	v_mov_b32_e32 v147, 0
	v_mov_b32_e32 v148, 0
	v_mov_b32_e32 v149, 0
	v_mov_b32_e32 v150, 0
	v_mov_b32_e32 v151, 0
	ds_read_b32 v152, v137 offset:0
	ds_read_b32 v153, v137 offset:4160
	ds_read_b32 v154, v138 offset:0
	ds_read_b32 v155, v138 offset:16900
	ds_read_b32 v156, v138 offset:4160
	ds_read_b32 v157, v138 offset:21060
	ds_read_b32 v158, v137 offset:16
	ds_read_b32 v159, v137 offset:4176
	ds_read_b32 v160, v138 offset:16
	ds_read_b32 v161, v138 offset:16916
	ds_read_b32 v162, v138 offset:4176
	ds_read_b32 v163, v138 offset:21076
	s_waitcnt lgkmcnt(6)
	v_mul_f32_e32 v172, v153, v155
	v_mul_f32_e32 v173, v152, v155
	v_fma_f32 v164, v152, v154, -v172
	v_fma_f32 v165, -v153, v154, -v173
	v_mul_f32_e32 v172, v153, v157
	v_mul_f32_e32 v173, v152, v157
	v_fma_f32 v166, v152, v156, -v172
	v_fma_f32 v167, -v153, v156, -v173
	s_nop 1
	v_mfma_f32_16x16x4_f32 v[144:147], v100, v164, v[144:147]
	v_mfma_f32_16x16x4_f32 v[148:151], v100, v166, v[148:151]
	v_mfma_f32_16x16x4_f32 v[144:147], v116, v165, v[144:147]
	v_mfma_f32_16x16x4_f32 v[148:151], v116, v167, v[148:151]
	ds_read_b32 v152, v137 offset:32
	ds_read_b32 v153, v137 offset:4192
	ds_read_b32 v154, v138 offset:32
	ds_read_b32 v155, v138 offset:16932
	ds_read_b32 v156, v138 offset:4192
	ds_read_b32 v157, v138 offset:21092
	s_waitcnt lgkmcnt(6)
	v_mul_f32_e32 v172, v159, v161
	v_mul_f32_e32 v173, v158, v161
	v_fma_f32 v168, v158, v160, -v172
	v_fma_f32 v169, -v159, v160, -v173
	v_mul_f32_e32 v172, v159, v163
	v_mul_f32_e32 v173, v158, v163
	v_fma_f32 v170, v158, v162, -v172
	v_fma_f32 v171, -v159, v162, -v173
	s_nop 1
	v_mfma_f32_16x16x4_f32 v[144:147], v101, v168, v[144:147]
	v_mfma_f32_16x16x4_f32 v[148:151], v101, v170, v[148:151]
	v_mfma_f32_16x16x4_f32 v[144:147], v117, v169, v[144:147]
	v_mfma_f32_16x16x4_f32 v[148:151], v117, v171, v[148:151]
	ds_read_b32 v158, v137 offset:48
	ds_read_b32 v159, v137 offset:4208
	ds_read_b32 v160, v138 offset:48
	ds_read_b32 v161, v138 offset:16948
	ds_read_b32 v162, v138 offset:4208
	ds_read_b32 v163, v138 offset:21108
	s_waitcnt lgkmcnt(6)
	v_mul_f32_e32 v172, v153, v155
	v_mul_f32_e32 v173, v152, v155
	v_fma_f32 v164, v152, v154, -v172
	v_fma_f32 v165, -v153, v154, -v173
	v_mul_f32_e32 v172, v153, v157
	v_mul_f32_e32 v173, v152, v157
	v_fma_f32 v166, v152, v156, -v172
	v_fma_f32 v167, -v153, v156, -v173
	s_nop 1
	v_mfma_f32_16x16x4_f32 v[144:147], v102, v164, v[144:147]
	v_mfma_f32_16x16x4_f32 v[148:151], v102, v166, v[148:151]
	v_mfma_f32_16x16x4_f32 v[144:147], v118, v165, v[144:147]
	v_mfma_f32_16x16x4_f32 v[148:151], v118, v167, v[148:151]
	ds_read_b32 v152, v137 offset:64
	ds_read_b32 v153, v137 offset:4224
	ds_read_b32 v154, v138 offset:64
	ds_read_b32 v155, v138 offset:16964
	ds_read_b32 v156, v138 offset:4224
	ds_read_b32 v157, v138 offset:21124
	s_waitcnt lgkmcnt(6)
	v_mul_f32_e32 v172, v159, v161
	v_mul_f32_e32 v173, v158, v161
	v_fma_f32 v168, v158, v160, -v172
	v_fma_f32 v169, -v159, v160, -v173
	v_mul_f32_e32 v172, v159, v163
	v_mul_f32_e32 v173, v158, v163
	v_fma_f32 v170, v158, v162, -v172
	v_fma_f32 v171, -v159, v162, -v173
	s_nop 1
	v_mfma_f32_16x16x4_f32 v[144:147], v103, v168, v[144:147]
	v_mfma_f32_16x16x4_f32 v[148:151], v103, v170, v[148:151]
	v_mfma_f32_16x16x4_f32 v[144:147], v119, v169, v[144:147]
	v_mfma_f32_16x16x4_f32 v[148:151], v119, v171, v[148:151]
	ds_read_b32 v158, v137 offset:80
	ds_read_b32 v159, v137 offset:4240
	ds_read_b32 v160, v138 offset:80
	ds_read_b32 v161, v138 offset:16980
	ds_read_b32 v162, v138 offset:4240
	ds_read_b32 v163, v138 offset:21140
	s_waitcnt lgkmcnt(6)
	v_mul_f32_e32 v172, v153, v155
	v_mul_f32_e32 v173, v152, v155
	v_fma_f32 v164, v152, v154, -v172
	v_fma_f32 v165, -v153, v154, -v173
	v_mul_f32_e32 v172, v153, v157
	v_mul_f32_e32 v173, v152, v157
	v_fma_f32 v166, v152, v156, -v172
	v_fma_f32 v167, -v153, v156, -v173
	s_nop 1
	v_mfma_f32_16x16x4_f32 v[144:147], v104, v164, v[144:147]
	v_mfma_f32_16x16x4_f32 v[148:151], v104, v166, v[148:151]
	v_mfma_f32_16x16x4_f32 v[144:147], v120, v165, v[144:147]
	v_mfma_f32_16x16x4_f32 v[148:151], v120, v167, v[148:151]
	ds_read_b32 v152, v137 offset:96
	ds_read_b32 v153, v137 offset:4256
	ds_read_b32 v154, v138 offset:96
	ds_read_b32 v155, v138 offset:16996
	ds_read_b32 v156, v138 offset:4256
	ds_read_b32 v157, v138 offset:21156
	s_waitcnt lgkmcnt(6)
	v_mul_f32_e32 v172, v159, v161
	v_mul_f32_e32 v173, v158, v161
	v_fma_f32 v168, v158, v160, -v172
	v_fma_f32 v169, -v159, v160, -v173
	v_mul_f32_e32 v172, v159, v163
	v_mul_f32_e32 v173, v158, v163
	v_fma_f32 v170, v158, v162, -v172
	v_fma_f32 v171, -v159, v162, -v173
	s_nop 1
	v_mfma_f32_16x16x4_f32 v[144:147], v105, v168, v[144:147]
	v_mfma_f32_16x16x4_f32 v[148:151], v105, v170, v[148:151]
	v_mfma_f32_16x16x4_f32 v[144:147], v121, v169, v[144:147]
	v_mfma_f32_16x16x4_f32 v[148:151], v121, v171, v[148:151]
	ds_read_b32 v158, v137 offset:112
	ds_read_b32 v159, v137 offset:4272
	ds_read_b32 v160, v138 offset:112
	ds_read_b32 v161, v138 offset:17012
	ds_read_b32 v162, v138 offset:4272
	ds_read_b32 v163, v138 offset:21172
	s_waitcnt lgkmcnt(6)
	v_mul_f32_e32 v172, v153, v155
	v_mul_f32_e32 v173, v152, v155
	v_fma_f32 v164, v152, v154, -v172
	v_fma_f32 v165, -v153, v154, -v173
	v_mul_f32_e32 v172, v153, v157
	v_mul_f32_e32 v173, v152, v157
	v_fma_f32 v166, v152, v156, -v172
	v_fma_f32 v167, -v153, v156, -v173
	s_nop 1
	v_mfma_f32_16x16x4_f32 v[144:147], v106, v164, v[144:147]
	v_mfma_f32_16x16x4_f32 v[148:151], v106, v166, v[148:151]
	v_mfma_f32_16x16x4_f32 v[144:147], v122, v165, v[144:147]
	v_mfma_f32_16x16x4_f32 v[148:151], v122, v167, v[148:151]
	ds_read_b32 v152, v137 offset:128
	ds_read_b32 v153, v137 offset:4288
	ds_read_b32 v154, v138 offset:128
	ds_read_b32 v155, v138 offset:17028
	ds_read_b32 v156, v138 offset:4288
	ds_read_b32 v157, v138 offset:21188
	s_waitcnt lgkmcnt(6)
	v_mul_f32_e32 v172, v159, v161
	v_mul_f32_e32 v173, v158, v161
	v_fma_f32 v168, v158, v160, -v172
	v_fma_f32 v169, -v159, v160, -v173
	v_mul_f32_e32 v172, v159, v163
	v_mul_f32_e32 v173, v158, v163
	v_fma_f32 v170, v158, v162, -v172
	v_fma_f32 v171, -v159, v162, -v173
	s_nop 1
	v_mfma_f32_16x16x4_f32 v[144:147], v107, v168, v[144:147]
	v_mfma_f32_16x16x4_f32 v[148:151], v107, v170, v[148:151]
	v_mfma_f32_16x16x4_f32 v[144:147], v123, v169, v[144:147]
	v_mfma_f32_16x16x4_f32 v[148:151], v123, v171, v[148:151]
	ds_read_b32 v158, v137 offset:144
	ds_read_b32 v159, v137 offset:4304
	ds_read_b32 v160, v138 offset:144
	ds_read_b32 v161, v138 offset:17044
	ds_read_b32 v162, v138 offset:4304
	ds_read_b32 v163, v138 offset:21204
	s_waitcnt lgkmcnt(6)
	v_mul_f32_e32 v172, v153, v155
	v_mul_f32_e32 v173, v152, v155
	v_fma_f32 v164, v152, v154, -v172
	v_fma_f32 v165, -v153, v154, -v173
	v_mul_f32_e32 v172, v153, v157
	v_mul_f32_e32 v173, v152, v157
	v_fma_f32 v166, v152, v156, -v172
	v_fma_f32 v167, -v153, v156, -v173
	s_nop 1
	v_mfma_f32_16x16x4_f32 v[144:147], v108, v164, v[144:147]
	v_mfma_f32_16x16x4_f32 v[148:151], v108, v166, v[148:151]
	v_mfma_f32_16x16x4_f32 v[144:147], v124, v165, v[144:147]
	v_mfma_f32_16x16x4_f32 v[148:151], v124, v167, v[148:151]
	ds_read_b32 v152, v137 offset:160
	ds_read_b32 v153, v137 offset:4320
	ds_read_b32 v154, v138 offset:160
	ds_read_b32 v155, v138 offset:17060
	ds_read_b32 v156, v138 offset:4320
	ds_read_b32 v157, v138 offset:21220
	s_waitcnt lgkmcnt(6)
	v_mul_f32_e32 v172, v159, v161
	v_mul_f32_e32 v173, v158, v161
	v_fma_f32 v168, v158, v160, -v172
	v_fma_f32 v169, -v159, v160, -v173
	v_mul_f32_e32 v172, v159, v163
	v_mul_f32_e32 v173, v158, v163
	v_fma_f32 v170, v158, v162, -v172
	v_fma_f32 v171, -v159, v162, -v173
	s_nop 1
	v_mfma_f32_16x16x4_f32 v[144:147], v109, v168, v[144:147]
	v_mfma_f32_16x16x4_f32 v[148:151], v109, v170, v[148:151]
	v_mfma_f32_16x16x4_f32 v[144:147], v125, v169, v[144:147]
	v_mfma_f32_16x16x4_f32 v[148:151], v125, v171, v[148:151]
	ds_read_b32 v158, v137 offset:176
	ds_read_b32 v159, v137 offset:4336
	ds_read_b32 v160, v138 offset:176
	ds_read_b32 v161, v138 offset:17076
	ds_read_b32 v162, v138 offset:4336
	ds_read_b32 v163, v138 offset:21236
	s_waitcnt lgkmcnt(6)
	v_mul_f32_e32 v172, v153, v155
	v_mul_f32_e32 v173, v152, v155
	v_fma_f32 v164, v152, v154, -v172
	v_fma_f32 v165, -v153, v154, -v173
	v_mul_f32_e32 v172, v153, v157
	v_mul_f32_e32 v173, v152, v157
	v_fma_f32 v166, v152, v156, -v172
	v_fma_f32 v167, -v153, v156, -v173
	s_nop 1
	v_mfma_f32_16x16x4_f32 v[144:147], v110, v164, v[144:147]
	v_mfma_f32_16x16x4_f32 v[148:151], v110, v166, v[148:151]
	v_mfma_f32_16x16x4_f32 v[144:147], v126, v165, v[144:147]
	v_mfma_f32_16x16x4_f32 v[148:151], v126, v167, v[148:151]
	ds_read_b32 v152, v137 offset:192
	ds_read_b32 v153, v137 offset:4352
	ds_read_b32 v154, v138 offset:192
	ds_read_b32 v155, v138 offset:17092
	ds_read_b32 v156, v138 offset:4352
	ds_read_b32 v157, v138 offset:21252
	s_waitcnt lgkmcnt(6)
	v_mul_f32_e32 v172, v159, v161
	v_mul_f32_e32 v173, v158, v161
	v_fma_f32 v168, v158, v160, -v172
	v_fma_f32 v169, -v159, v160, -v173
	v_mul_f32_e32 v172, v159, v163
	v_mul_f32_e32 v173, v158, v163
	v_fma_f32 v170, v158, v162, -v172
	v_fma_f32 v171, -v159, v162, -v173
	s_nop 1
	v_mfma_f32_16x16x4_f32 v[144:147], v111, v168, v[144:147]
	v_mfma_f32_16x16x4_f32 v[148:151], v111, v170, v[148:151]
	v_mfma_f32_16x16x4_f32 v[144:147], v127, v169, v[144:147]
	v_mfma_f32_16x16x4_f32 v[148:151], v127, v171, v[148:151]
	ds_read_b32 v158, v137 offset:208
	ds_read_b32 v159, v137 offset:4368
	ds_read_b32 v160, v138 offset:208
	ds_read_b32 v161, v138 offset:17108
	ds_read_b32 v162, v138 offset:4368
	ds_read_b32 v163, v138 offset:21268
	s_waitcnt lgkmcnt(6)
	v_mul_f32_e32 v172, v153, v155
	v_mul_f32_e32 v173, v152, v155
	v_fma_f32 v164, v152, v154, -v172
	v_fma_f32 v165, -v153, v154, -v173
	v_mul_f32_e32 v172, v153, v157
	v_mul_f32_e32 v173, v152, v157
	v_fma_f32 v166, v152, v156, -v172
	v_fma_f32 v167, -v153, v156, -v173
	s_nop 1
	v_mfma_f32_16x16x4_f32 v[144:147], v112, v164, v[144:147]
	v_mfma_f32_16x16x4_f32 v[148:151], v112, v166, v[148:151]
	v_mfma_f32_16x16x4_f32 v[144:147], v128, v165, v[144:147]
	v_mfma_f32_16x16x4_f32 v[148:151], v128, v167, v[148:151]
	ds_read_b32 v152, v137 offset:224
	ds_read_b32 v153, v137 offset:4384
	ds_read_b32 v154, v138 offset:224
	ds_read_b32 v155, v138 offset:17124
	ds_read_b32 v156, v138 offset:4384
	ds_read_b32 v157, v138 offset:21284
	s_waitcnt lgkmcnt(6)
	v_mul_f32_e32 v172, v159, v161
	v_mul_f32_e32 v173, v158, v161
	v_fma_f32 v168, v158, v160, -v172
	v_fma_f32 v169, -v159, v160, -v173
	v_mul_f32_e32 v172, v159, v163
	v_mul_f32_e32 v173, v158, v163
	v_fma_f32 v170, v158, v162, -v172
	v_fma_f32 v171, -v159, v162, -v173
	s_nop 1
	v_mfma_f32_16x16x4_f32 v[144:147], v113, v168, v[144:147]
	v_mfma_f32_16x16x4_f32 v[148:151], v113, v170, v[148:151]
	v_mfma_f32_16x16x4_f32 v[144:147], v129, v169, v[144:147]
	v_mfma_f32_16x16x4_f32 v[148:151], v129, v171, v[148:151]
	ds_read_b32 v158, v137 offset:240
	ds_read_b32 v159, v137 offset:4400
	ds_read_b32 v160, v138 offset:240
	ds_read_b32 v161, v138 offset:17140
	ds_read_b32 v162, v138 offset:4400
	ds_read_b32 v163, v138 offset:21300
	s_waitcnt lgkmcnt(6)
	v_mul_f32_e32 v172, v153, v155
	v_mul_f32_e32 v173, v152, v155
	v_fma_f32 v164, v152, v154, -v172
	v_fma_f32 v165, -v153, v154, -v173
	v_mul_f32_e32 v172, v153, v157
	v_mul_f32_e32 v173, v152, v157
	v_fma_f32 v166, v152, v156, -v172
	v_fma_f32 v167, -v153, v156, -v173
	s_nop 1
	v_mfma_f32_16x16x4_f32 v[144:147], v114, v164, v[144:147]
	v_mfma_f32_16x16x4_f32 v[148:151], v114, v166, v[148:151]
	v_mfma_f32_16x16x4_f32 v[144:147], v130, v165, v[144:147]
	v_mfma_f32_16x16x4_f32 v[148:151], v130, v167, v[148:151]
	s_waitcnt lgkmcnt(0)
	v_mul_f32_e32 v172, v159, v161
	v_mul_f32_e32 v173, v158, v161
	v_fma_f32 v168, v158, v160, -v172
	v_fma_f32 v169, -v159, v160, -v173
	v_mul_f32_e32 v172, v159, v163
	v_mul_f32_e32 v173, v158, v163
	v_fma_f32 v170, v158, v162, -v172
	v_fma_f32 v171, -v159, v162, -v173
	s_nop 1
	v_mfma_f32_16x16x4_f32 v[144:147], v115, v168, v[144:147]
	v_mfma_f32_16x16x4_f32 v[148:151], v115, v170, v[148:151]
	v_mfma_f32_16x16x4_f32 v[144:147], v131, v169, v[144:147]
	v_mfma_f32_16x16x4_f32 v[148:151], v131, v171, v[148:151]
	v_subrev_u32_e32 v138, 0x2080, v138
	v_add_u32_e32 v137, 0x820, v137
	s_nop 9
	v_cvt_pk_bf16_f32 v174, v144, v145
	v_cvt_pk_bf16_f32 v175, v146, v147
	v_cvt_pk_bf16_f32 v176, v148, v149
	v_cvt_pk_bf16_f32 v177, v150, v151
	global_store_dwordx2 v[140:141], v[174:175], off
	global_store_dwordx2 v[140:141], v[176:177], off offset:512
	v_add_co_u32_e32 v140, vcc, 0x3c00, v140
	s_nop 1
	v_addc_co_u32_e32 v141, vcc, 0, v141, vcc
	v_mov_b32_e32 v144, 0
	v_mov_b32_e32 v145, 0
	v_mov_b32_e32 v146, 0
	v_mov_b32_e32 v147, 0
	v_mov_b32_e32 v148, 0
	v_mov_b32_e32 v149, 0
	v_mov_b32_e32 v150, 0
	v_mov_b32_e32 v151, 0
	ds_read_b32 v152, v137 offset:0
	ds_read_b32 v153, v137 offset:4160
	ds_read_b32 v154, v138 offset:0
	ds_read_b32 v155, v138 offset:16900
	ds_read_b32 v156, v138 offset:4160
	ds_read_b32 v157, v138 offset:21060
	ds_read_b32 v158, v137 offset:16
	ds_read_b32 v159, v137 offset:4176
	ds_read_b32 v160, v138 offset:16
	ds_read_b32 v161, v138 offset:16916
	ds_read_b32 v162, v138 offset:4176
	ds_read_b32 v163, v138 offset:21076
	s_waitcnt lgkmcnt(6)
	v_mul_f32_e32 v172, v153, v155
	v_mul_f32_e32 v173, v152, v155
	v_fma_f32 v164, v152, v154, -v172
	v_fma_f32 v165, -v153, v154, -v173
	v_mul_f32_e32 v172, v153, v157
	v_mul_f32_e32 v173, v152, v157
	v_fma_f32 v166, v152, v156, -v172
	v_fma_f32 v167, -v153, v156, -v173
	s_nop 1
	v_mfma_f32_16x16x4_f32 v[144:147], v100, v164, v[144:147]
	v_mfma_f32_16x16x4_f32 v[148:151], v100, v166, v[148:151]
	v_mfma_f32_16x16x4_f32 v[144:147], v116, v165, v[144:147]
	v_mfma_f32_16x16x4_f32 v[148:151], v116, v167, v[148:151]
	ds_read_b32 v152, v137 offset:32
	ds_read_b32 v153, v137 offset:4192
	ds_read_b32 v154, v138 offset:32
	ds_read_b32 v155, v138 offset:16932
	ds_read_b32 v156, v138 offset:4192
	ds_read_b32 v157, v138 offset:21092
	s_waitcnt lgkmcnt(6)
	v_mul_f32_e32 v172, v159, v161
	v_mul_f32_e32 v173, v158, v161
	v_fma_f32 v168, v158, v160, -v172
	v_fma_f32 v169, -v159, v160, -v173
	v_mul_f32_e32 v172, v159, v163
	v_mul_f32_e32 v173, v158, v163
	v_fma_f32 v170, v158, v162, -v172
	v_fma_f32 v171, -v159, v162, -v173
	s_nop 1
	v_mfma_f32_16x16x4_f32 v[144:147], v101, v168, v[144:147]
	v_mfma_f32_16x16x4_f32 v[148:151], v101, v170, v[148:151]
	v_mfma_f32_16x16x4_f32 v[144:147], v117, v169, v[144:147]
	v_mfma_f32_16x16x4_f32 v[148:151], v117, v171, v[148:151]
	ds_read_b32 v158, v137 offset:48
	ds_read_b32 v159, v137 offset:4208
	ds_read_b32 v160, v138 offset:48
	ds_read_b32 v161, v138 offset:16948
	ds_read_b32 v162, v138 offset:4208
	ds_read_b32 v163, v138 offset:21108
	s_waitcnt lgkmcnt(6)
	v_mul_f32_e32 v172, v153, v155
	v_mul_f32_e32 v173, v152, v155
	v_fma_f32 v164, v152, v154, -v172
	v_fma_f32 v165, -v153, v154, -v173
	v_mul_f32_e32 v172, v153, v157
	v_mul_f32_e32 v173, v152, v157
	v_fma_f32 v166, v152, v156, -v172
	v_fma_f32 v167, -v153, v156, -v173
	s_nop 1
	v_mfma_f32_16x16x4_f32 v[144:147], v102, v164, v[144:147]
	v_mfma_f32_16x16x4_f32 v[148:151], v102, v166, v[148:151]
	v_mfma_f32_16x16x4_f32 v[144:147], v118, v165, v[144:147]
	v_mfma_f32_16x16x4_f32 v[148:151], v118, v167, v[148:151]
	ds_read_b32 v152, v137 offset:64
	ds_read_b32 v153, v137 offset:4224
	ds_read_b32 v154, v138 offset:64
	ds_read_b32 v155, v138 offset:16964
	ds_read_b32 v156, v138 offset:4224
	ds_read_b32 v157, v138 offset:21124
	s_waitcnt lgkmcnt(6)
	v_mul_f32_e32 v172, v159, v161
	v_mul_f32_e32 v173, v158, v161
	v_fma_f32 v168, v158, v160, -v172
	v_fma_f32 v169, -v159, v160, -v173
	v_mul_f32_e32 v172, v159, v163
	v_mul_f32_e32 v173, v158, v163
	v_fma_f32 v170, v158, v162, -v172
	v_fma_f32 v171, -v159, v162, -v173
	s_nop 1
	v_mfma_f32_16x16x4_f32 v[144:147], v103, v168, v[144:147]
	v_mfma_f32_16x16x4_f32 v[148:151], v103, v170, v[148:151]
	v_mfma_f32_16x16x4_f32 v[144:147], v119, v169, v[144:147]
	v_mfma_f32_16x16x4_f32 v[148:151], v119, v171, v[148:151]
	ds_read_b32 v158, v137 offset:80
	ds_read_b32 v159, v137 offset:4240
	ds_read_b32 v160, v138 offset:80
	ds_read_b32 v161, v138 offset:16980
	ds_read_b32 v162, v138 offset:4240
	ds_read_b32 v163, v138 offset:21140
	s_waitcnt lgkmcnt(6)
	v_mul_f32_e32 v172, v153, v155
	v_mul_f32_e32 v173, v152, v155
	v_fma_f32 v164, v152, v154, -v172
	v_fma_f32 v165, -v153, v154, -v173
	v_mul_f32_e32 v172, v153, v157
	v_mul_f32_e32 v173, v152, v157
	v_fma_f32 v166, v152, v156, -v172
	v_fma_f32 v167, -v153, v156, -v173
	s_nop 1
	v_mfma_f32_16x16x4_f32 v[144:147], v104, v164, v[144:147]
	v_mfma_f32_16x16x4_f32 v[148:151], v104, v166, v[148:151]
	v_mfma_f32_16x16x4_f32 v[144:147], v120, v165, v[144:147]
	v_mfma_f32_16x16x4_f32 v[148:151], v120, v167, v[148:151]
	ds_read_b32 v152, v137 offset:96
	ds_read_b32 v153, v137 offset:4256
	ds_read_b32 v154, v138 offset:96
	ds_read_b32 v155, v138 offset:16996
	ds_read_b32 v156, v138 offset:4256
	ds_read_b32 v157, v138 offset:21156
	s_waitcnt lgkmcnt(6)
	v_mul_f32_e32 v172, v159, v161
	v_mul_f32_e32 v173, v158, v161
	v_fma_f32 v168, v158, v160, -v172
	v_fma_f32 v169, -v159, v160, -v173
	v_mul_f32_e32 v172, v159, v163
	v_mul_f32_e32 v173, v158, v163
	v_fma_f32 v170, v158, v162, -v172
	v_fma_f32 v171, -v159, v162, -v173
	s_nop 1
	v_mfma_f32_16x16x4_f32 v[144:147], v105, v168, v[144:147]
	v_mfma_f32_16x16x4_f32 v[148:151], v105, v170, v[148:151]
	v_mfma_f32_16x16x4_f32 v[144:147], v121, v169, v[144:147]
	v_mfma_f32_16x16x4_f32 v[148:151], v121, v171, v[148:151]
	ds_read_b32 v158, v137 offset:112
	ds_read_b32 v159, v137 offset:4272
	ds_read_b32 v160, v138 offset:112
	ds_read_b32 v161, v138 offset:17012
	ds_read_b32 v162, v138 offset:4272
	ds_read_b32 v163, v138 offset:21172
	s_waitcnt lgkmcnt(6)
	v_mul_f32_e32 v172, v153, v155
	v_mul_f32_e32 v173, v152, v155
	v_fma_f32 v164, v152, v154, -v172
	v_fma_f32 v165, -v153, v154, -v173
	v_mul_f32_e32 v172, v153, v157
	v_mul_f32_e32 v173, v152, v157
	v_fma_f32 v166, v152, v156, -v172
	v_fma_f32 v167, -v153, v156, -v173
	s_nop 1
	v_mfma_f32_16x16x4_f32 v[144:147], v106, v164, v[144:147]
	v_mfma_f32_16x16x4_f32 v[148:151], v106, v166, v[148:151]
	v_mfma_f32_16x16x4_f32 v[144:147], v122, v165, v[144:147]
	v_mfma_f32_16x16x4_f32 v[148:151], v122, v167, v[148:151]
	ds_read_b32 v152, v137 offset:128
	ds_read_b32 v153, v137 offset:4288
	ds_read_b32 v154, v138 offset:128
	ds_read_b32 v155, v138 offset:17028
	ds_read_b32 v156, v138 offset:4288
	ds_read_b32 v157, v138 offset:21188
	s_waitcnt lgkmcnt(6)
	v_mul_f32_e32 v172, v159, v161
	v_mul_f32_e32 v173, v158, v161
	v_fma_f32 v168, v158, v160, -v172
	v_fma_f32 v169, -v159, v160, -v173
	v_mul_f32_e32 v172, v159, v163
	v_mul_f32_e32 v173, v158, v163
	v_fma_f32 v170, v158, v162, -v172
	v_fma_f32 v171, -v159, v162, -v173
	s_nop 1
	v_mfma_f32_16x16x4_f32 v[144:147], v107, v168, v[144:147]
	v_mfma_f32_16x16x4_f32 v[148:151], v107, v170, v[148:151]
	v_mfma_f32_16x16x4_f32 v[144:147], v123, v169, v[144:147]
	v_mfma_f32_16x16x4_f32 v[148:151], v123, v171, v[148:151]
	ds_read_b32 v158, v137 offset:144
	ds_read_b32 v159, v137 offset:4304
	ds_read_b32 v160, v138 offset:144
	ds_read_b32 v161, v138 offset:17044
	ds_read_b32 v162, v138 offset:4304
	ds_read_b32 v163, v138 offset:21204
	s_waitcnt lgkmcnt(6)
	v_mul_f32_e32 v172, v153, v155
	v_mul_f32_e32 v173, v152, v155
	v_fma_f32 v164, v152, v154, -v172
	v_fma_f32 v165, -v153, v154, -v173
	v_mul_f32_e32 v172, v153, v157
	v_mul_f32_e32 v173, v152, v157
	v_fma_f32 v166, v152, v156, -v172
	v_fma_f32 v167, -v153, v156, -v173
	s_nop 1
	v_mfma_f32_16x16x4_f32 v[144:147], v108, v164, v[144:147]
	v_mfma_f32_16x16x4_f32 v[148:151], v108, v166, v[148:151]
	v_mfma_f32_16x16x4_f32 v[144:147], v124, v165, v[144:147]
	v_mfma_f32_16x16x4_f32 v[148:151], v124, v167, v[148:151]
	ds_read_b32 v152, v137 offset:160
	ds_read_b32 v153, v137 offset:4320
	ds_read_b32 v154, v138 offset:160
	ds_read_b32 v155, v138 offset:17060
	ds_read_b32 v156, v138 offset:4320
	ds_read_b32 v157, v138 offset:21220
	s_waitcnt lgkmcnt(6)
	v_mul_f32_e32 v172, v159, v161
	v_mul_f32_e32 v173, v158, v161
	v_fma_f32 v168, v158, v160, -v172
	v_fma_f32 v169, -v159, v160, -v173
	v_mul_f32_e32 v172, v159, v163
	v_mul_f32_e32 v173, v158, v163
	v_fma_f32 v170, v158, v162, -v172
	v_fma_f32 v171, -v159, v162, -v173
	s_nop 1
	v_mfma_f32_16x16x4_f32 v[144:147], v109, v168, v[144:147]
	v_mfma_f32_16x16x4_f32 v[148:151], v109, v170, v[148:151]
	v_mfma_f32_16x16x4_f32 v[144:147], v125, v169, v[144:147]
	v_mfma_f32_16x16x4_f32 v[148:151], v125, v171, v[148:151]
	ds_read_b32 v158, v137 offset:176
	ds_read_b32 v159, v137 offset:4336
	ds_read_b32 v160, v138 offset:176
	ds_read_b32 v161, v138 offset:17076
	ds_read_b32 v162, v138 offset:4336
	ds_read_b32 v163, v138 offset:21236
	s_waitcnt lgkmcnt(6)
	v_mul_f32_e32 v172, v153, v155
	v_mul_f32_e32 v173, v152, v155
	v_fma_f32 v164, v152, v154, -v172
	v_fma_f32 v165, -v153, v154, -v173
	v_mul_f32_e32 v172, v153, v157
	v_mul_f32_e32 v173, v152, v157
	v_fma_f32 v166, v152, v156, -v172
	v_fma_f32 v167, -v153, v156, -v173
	s_nop 1
	v_mfma_f32_16x16x4_f32 v[144:147], v110, v164, v[144:147]
	v_mfma_f32_16x16x4_f32 v[148:151], v110, v166, v[148:151]
	v_mfma_f32_16x16x4_f32 v[144:147], v126, v165, v[144:147]
	v_mfma_f32_16x16x4_f32 v[148:151], v126, v167, v[148:151]
	ds_read_b32 v152, v137 offset:192
	ds_read_b32 v153, v137 offset:4352
	ds_read_b32 v154, v138 offset:192
	ds_read_b32 v155, v138 offset:17092
	ds_read_b32 v156, v138 offset:4352
	ds_read_b32 v157, v138 offset:21252
	s_waitcnt lgkmcnt(6)
	v_mul_f32_e32 v172, v159, v161
	v_mul_f32_e32 v173, v158, v161
	v_fma_f32 v168, v158, v160, -v172
	v_fma_f32 v169, -v159, v160, -v173
	v_mul_f32_e32 v172, v159, v163
	v_mul_f32_e32 v173, v158, v163
	v_fma_f32 v170, v158, v162, -v172
	v_fma_f32 v171, -v159, v162, -v173
	s_nop 1
	v_mfma_f32_16x16x4_f32 v[144:147], v111, v168, v[144:147]
	v_mfma_f32_16x16x4_f32 v[148:151], v111, v170, v[148:151]
	v_mfma_f32_16x16x4_f32 v[144:147], v127, v169, v[144:147]
	v_mfma_f32_16x16x4_f32 v[148:151], v127, v171, v[148:151]
	ds_read_b32 v158, v137 offset:208
	ds_read_b32 v159, v137 offset:4368
	ds_read_b32 v160, v138 offset:208
	ds_read_b32 v161, v138 offset:17108
	ds_read_b32 v162, v138 offset:4368
	ds_read_b32 v163, v138 offset:21268
	s_waitcnt lgkmcnt(6)
	v_mul_f32_e32 v172, v153, v155
	v_mul_f32_e32 v173, v152, v155
	v_fma_f32 v164, v152, v154, -v172
	v_fma_f32 v165, -v153, v154, -v173
	v_mul_f32_e32 v172, v153, v157
	v_mul_f32_e32 v173, v152, v157
	v_fma_f32 v166, v152, v156, -v172
	v_fma_f32 v167, -v153, v156, -v173
	s_nop 1
	v_mfma_f32_16x16x4_f32 v[144:147], v112, v164, v[144:147]
	v_mfma_f32_16x16x4_f32 v[148:151], v112, v166, v[148:151]
	v_mfma_f32_16x16x4_f32 v[144:147], v128, v165, v[144:147]
	v_mfma_f32_16x16x4_f32 v[148:151], v128, v167, v[148:151]
	ds_read_b32 v152, v137 offset:224
	ds_read_b32 v153, v137 offset:4384
	ds_read_b32 v154, v138 offset:224
	ds_read_b32 v155, v138 offset:17124
	ds_read_b32 v156, v138 offset:4384
	ds_read_b32 v157, v138 offset:21284
	s_waitcnt lgkmcnt(6)
	v_mul_f32_e32 v172, v159, v161
	v_mul_f32_e32 v173, v158, v161
	v_fma_f32 v168, v158, v160, -v172
	v_fma_f32 v169, -v159, v160, -v173
	v_mul_f32_e32 v172, v159, v163
	v_mul_f32_e32 v173, v158, v163
	v_fma_f32 v170, v158, v162, -v172
	v_fma_f32 v171, -v159, v162, -v173
	s_nop 1
	v_mfma_f32_16x16x4_f32 v[144:147], v113, v168, v[144:147]
	v_mfma_f32_16x16x4_f32 v[148:151], v113, v170, v[148:151]
	v_mfma_f32_16x16x4_f32 v[144:147], v129, v169, v[144:147]
	v_mfma_f32_16x16x4_f32 v[148:151], v129, v171, v[148:151]
	ds_read_b32 v158, v137 offset:240
	ds_read_b32 v159, v137 offset:4400
	ds_read_b32 v160, v138 offset:240
	ds_read_b32 v161, v138 offset:17140
	ds_read_b32 v162, v138 offset:4400
	ds_read_b32 v163, v138 offset:21300
	s_waitcnt lgkmcnt(6)
	v_mul_f32_e32 v172, v153, v155
	v_mul_f32_e32 v173, v152, v155
	v_fma_f32 v164, v152, v154, -v172
	v_fma_f32 v165, -v153, v154, -v173
	v_mul_f32_e32 v172, v153, v157
	v_mul_f32_e32 v173, v152, v157
	v_fma_f32 v166, v152, v156, -v172
	v_fma_f32 v167, -v153, v156, -v173
	s_nop 1
	v_mfma_f32_16x16x4_f32 v[144:147], v114, v164, v[144:147]
	v_mfma_f32_16x16x4_f32 v[148:151], v114, v166, v[148:151]
	v_mfma_f32_16x16x4_f32 v[144:147], v130, v165, v[144:147]
	v_mfma_f32_16x16x4_f32 v[148:151], v130, v167, v[148:151]
	s_waitcnt lgkmcnt(0)
	v_mul_f32_e32 v172, v159, v161
	v_mul_f32_e32 v173, v158, v161
	v_fma_f32 v168, v158, v160, -v172
	v_fma_f32 v169, -v159, v160, -v173
	v_mul_f32_e32 v172, v159, v163
	v_mul_f32_e32 v173, v158, v163
	v_fma_f32 v170, v158, v162, -v172
	v_fma_f32 v171, -v159, v162, -v173
	s_nop 1
	v_mfma_f32_16x16x4_f32 v[144:147], v115, v168, v[144:147]
	v_mfma_f32_16x16x4_f32 v[148:151], v115, v170, v[148:151]
	v_mfma_f32_16x16x4_f32 v[144:147], v131, v169, v[144:147]
	v_mfma_f32_16x16x4_f32 v[148:151], v131, v171, v[148:151]
	v_add_u32_e32 v138, 0x2080, v138
	s_nop 9
	v_cvt_pk_bf16_f32 v174, v144, v145
	v_cvt_pk_bf16_f32 v175, v146, v147
	v_cvt_pk_bf16_f32 v176, v148, v149
	v_cvt_pk_bf16_f32 v177, v150, v151
	global_store_dwordx2 v[140:141], v[174:175], off
	global_store_dwordx2 v[140:141], v[176:177], off offset:512
	v_add_co_u32_e32 v140, vcc, 0x400, v140
	s_nop 1
	v_addc_co_u32_e32 v141, vcc, 0, v141, vcc
	v_mov_b32_e32 v144, 0
	v_mov_b32_e32 v145, 0
	v_mov_b32_e32 v146, 0
	v_mov_b32_e32 v147, 0
	v_mov_b32_e32 v148, 0
	v_mov_b32_e32 v149, 0
	v_mov_b32_e32 v150, 0
	v_mov_b32_e32 v151, 0
	ds_read_b32 v152, v137 offset:0
	ds_read_b32 v153, v137 offset:4160
	ds_read_b32 v154, v138 offset:0
	ds_read_b32 v155, v138 offset:16900
	ds_read_b32 v156, v138 offset:4160
	ds_read_b32 v157, v138 offset:21060
	ds_read_b32 v158, v137 offset:16
	ds_read_b32 v159, v137 offset:4176
	ds_read_b32 v160, v138 offset:16
	ds_read_b32 v161, v138 offset:16916
	ds_read_b32 v162, v138 offset:4176
	ds_read_b32 v163, v138 offset:21076
	s_waitcnt lgkmcnt(6)
	v_mul_f32_e32 v172, v153, v155
	v_mul_f32_e32 v173, v152, v155
	v_fma_f32 v164, v152, v154, -v172
	v_fma_f32 v165, -v153, v154, -v173
	v_mul_f32_e32 v172, v153, v157
	v_mul_f32_e32 v173, v152, v157
	v_fma_f32 v166, v152, v156, -v172
	v_fma_f32 v167, -v153, v156, -v173
	s_nop 1
	v_mfma_f32_16x16x4_f32 v[144:147], v100, v164, v[144:147]
	v_mfma_f32_16x16x4_f32 v[148:151], v100, v166, v[148:151]
	v_mfma_f32_16x16x4_f32 v[144:147], v116, v165, v[144:147]
	v_mfma_f32_16x16x4_f32 v[148:151], v116, v167, v[148:151]
	ds_read_b32 v152, v137 offset:32
	ds_read_b32 v153, v137 offset:4192
	ds_read_b32 v154, v138 offset:32
	ds_read_b32 v155, v138 offset:16932
	ds_read_b32 v156, v138 offset:4192
	ds_read_b32 v157, v138 offset:21092
	s_waitcnt lgkmcnt(6)
	v_mul_f32_e32 v172, v159, v161
	v_mul_f32_e32 v173, v158, v161
	v_fma_f32 v168, v158, v160, -v172
	v_fma_f32 v169, -v159, v160, -v173
	v_mul_f32_e32 v172, v159, v163
	v_mul_f32_e32 v173, v158, v163
	v_fma_f32 v170, v158, v162, -v172
	v_fma_f32 v171, -v159, v162, -v173
	s_nop 1
	v_mfma_f32_16x16x4_f32 v[144:147], v101, v168, v[144:147]
	v_mfma_f32_16x16x4_f32 v[148:151], v101, v170, v[148:151]
	v_mfma_f32_16x16x4_f32 v[144:147], v117, v169, v[144:147]
	v_mfma_f32_16x16x4_f32 v[148:151], v117, v171, v[148:151]
	ds_read_b32 v158, v137 offset:48
	ds_read_b32 v159, v137 offset:4208
	ds_read_b32 v160, v138 offset:48
	ds_read_b32 v161, v138 offset:16948
	ds_read_b32 v162, v138 offset:4208
	ds_read_b32 v163, v138 offset:21108
	s_waitcnt lgkmcnt(6)
	v_mul_f32_e32 v172, v153, v155
	v_mul_f32_e32 v173, v152, v155
	v_fma_f32 v164, v152, v154, -v172
	v_fma_f32 v165, -v153, v154, -v173
	v_mul_f32_e32 v172, v153, v157
	v_mul_f32_e32 v173, v152, v157
	v_fma_f32 v166, v152, v156, -v172
	v_fma_f32 v167, -v153, v156, -v173
	s_nop 1
	v_mfma_f32_16x16x4_f32 v[144:147], v102, v164, v[144:147]
	v_mfma_f32_16x16x4_f32 v[148:151], v102, v166, v[148:151]
	v_mfma_f32_16x16x4_f32 v[144:147], v118, v165, v[144:147]
	v_mfma_f32_16x16x4_f32 v[148:151], v118, v167, v[148:151]
	ds_read_b32 v152, v137 offset:64
	ds_read_b32 v153, v137 offset:4224
	ds_read_b32 v154, v138 offset:64
	ds_read_b32 v155, v138 offset:16964
	ds_read_b32 v156, v138 offset:4224
	ds_read_b32 v157, v138 offset:21124
	s_waitcnt lgkmcnt(6)
	v_mul_f32_e32 v172, v159, v161
	v_mul_f32_e32 v173, v158, v161
	v_fma_f32 v168, v158, v160, -v172
	v_fma_f32 v169, -v159, v160, -v173
	v_mul_f32_e32 v172, v159, v163
	v_mul_f32_e32 v173, v158, v163
	v_fma_f32 v170, v158, v162, -v172
	v_fma_f32 v171, -v159, v162, -v173
	s_nop 1
	v_mfma_f32_16x16x4_f32 v[144:147], v103, v168, v[144:147]
	v_mfma_f32_16x16x4_f32 v[148:151], v103, v170, v[148:151]
	v_mfma_f32_16x16x4_f32 v[144:147], v119, v169, v[144:147]
	v_mfma_f32_16x16x4_f32 v[148:151], v119, v171, v[148:151]
	ds_read_b32 v158, v137 offset:80
	ds_read_b32 v159, v137 offset:4240
	ds_read_b32 v160, v138 offset:80
	ds_read_b32 v161, v138 offset:16980
	ds_read_b32 v162, v138 offset:4240
	ds_read_b32 v163, v138 offset:21140
	s_waitcnt lgkmcnt(6)
	v_mul_f32_e32 v172, v153, v155
	v_mul_f32_e32 v173, v152, v155
	v_fma_f32 v164, v152, v154, -v172
	v_fma_f32 v165, -v153, v154, -v173
	v_mul_f32_e32 v172, v153, v157
	v_mul_f32_e32 v173, v152, v157
	v_fma_f32 v166, v152, v156, -v172
	v_fma_f32 v167, -v153, v156, -v173
	s_nop 1
	v_mfma_f32_16x16x4_f32 v[144:147], v104, v164, v[144:147]
	v_mfma_f32_16x16x4_f32 v[148:151], v104, v166, v[148:151]
	v_mfma_f32_16x16x4_f32 v[144:147], v120, v165, v[144:147]
	v_mfma_f32_16x16x4_f32 v[148:151], v120, v167, v[148:151]
	ds_read_b32 v152, v137 offset:96
	ds_read_b32 v153, v137 offset:4256
	ds_read_b32 v154, v138 offset:96
	ds_read_b32 v155, v138 offset:16996
	ds_read_b32 v156, v138 offset:4256
	ds_read_b32 v157, v138 offset:21156
	s_waitcnt lgkmcnt(6)
	v_mul_f32_e32 v172, v159, v161
	v_mul_f32_e32 v173, v158, v161
	v_fma_f32 v168, v158, v160, -v172
	v_fma_f32 v169, -v159, v160, -v173
	v_mul_f32_e32 v172, v159, v163
	v_mul_f32_e32 v173, v158, v163
	v_fma_f32 v170, v158, v162, -v172
	v_fma_f32 v171, -v159, v162, -v173
	s_nop 1
	v_mfma_f32_16x16x4_f32 v[144:147], v105, v168, v[144:147]
	v_mfma_f32_16x16x4_f32 v[148:151], v105, v170, v[148:151]
	v_mfma_f32_16x16x4_f32 v[144:147], v121, v169, v[144:147]
	v_mfma_f32_16x16x4_f32 v[148:151], v121, v171, v[148:151]
	ds_read_b32 v158, v137 offset:112
	ds_read_b32 v159, v137 offset:4272
	ds_read_b32 v160, v138 offset:112
	ds_read_b32 v161, v138 offset:17012
	ds_read_b32 v162, v138 offset:4272
	ds_read_b32 v163, v138 offset:21172
	s_waitcnt lgkmcnt(6)
	v_mul_f32_e32 v172, v153, v155
	v_mul_f32_e32 v173, v152, v155
	v_fma_f32 v164, v152, v154, -v172
	v_fma_f32 v165, -v153, v154, -v173
	v_mul_f32_e32 v172, v153, v157
	v_mul_f32_e32 v173, v152, v157
	v_fma_f32 v166, v152, v156, -v172
	v_fma_f32 v167, -v153, v156, -v173
	s_nop 1
	v_mfma_f32_16x16x4_f32 v[144:147], v106, v164, v[144:147]
	v_mfma_f32_16x16x4_f32 v[148:151], v106, v166, v[148:151]
	v_mfma_f32_16x16x4_f32 v[144:147], v122, v165, v[144:147]
	v_mfma_f32_16x16x4_f32 v[148:151], v122, v167, v[148:151]
	ds_read_b32 v152, v137 offset:128
	ds_read_b32 v153, v137 offset:4288
	ds_read_b32 v154, v138 offset:128
	ds_read_b32 v155, v138 offset:17028
	ds_read_b32 v156, v138 offset:4288
	ds_read_b32 v157, v138 offset:21188
	s_waitcnt lgkmcnt(6)
	v_mul_f32_e32 v172, v159, v161
	v_mul_f32_e32 v173, v158, v161
	v_fma_f32 v168, v158, v160, -v172
	v_fma_f32 v169, -v159, v160, -v173
	v_mul_f32_e32 v172, v159, v163
	v_mul_f32_e32 v173, v158, v163
	v_fma_f32 v170, v158, v162, -v172
	v_fma_f32 v171, -v159, v162, -v173
	s_nop 1
	v_mfma_f32_16x16x4_f32 v[144:147], v107, v168, v[144:147]
	v_mfma_f32_16x16x4_f32 v[148:151], v107, v170, v[148:151]
	v_mfma_f32_16x16x4_f32 v[144:147], v123, v169, v[144:147]
	v_mfma_f32_16x16x4_f32 v[148:151], v123, v171, v[148:151]
	ds_read_b32 v158, v137 offset:144
	ds_read_b32 v159, v137 offset:4304
	ds_read_b32 v160, v138 offset:144
	ds_read_b32 v161, v138 offset:17044
	ds_read_b32 v162, v138 offset:4304
	ds_read_b32 v163, v138 offset:21204
	s_waitcnt lgkmcnt(6)
	v_mul_f32_e32 v172, v153, v155
	v_mul_f32_e32 v173, v152, v155
	v_fma_f32 v164, v152, v154, -v172
	v_fma_f32 v165, -v153, v154, -v173
	v_mul_f32_e32 v172, v153, v157
	v_mul_f32_e32 v173, v152, v157
	v_fma_f32 v166, v152, v156, -v172
	v_fma_f32 v167, -v153, v156, -v173
	s_nop 1
	v_mfma_f32_16x16x4_f32 v[144:147], v108, v164, v[144:147]
	v_mfma_f32_16x16x4_f32 v[148:151], v108, v166, v[148:151]
	v_mfma_f32_16x16x4_f32 v[144:147], v124, v165, v[144:147]
	v_mfma_f32_16x16x4_f32 v[148:151], v124, v167, v[148:151]
	ds_read_b32 v152, v137 offset:160
	ds_read_b32 v153, v137 offset:4320
	ds_read_b32 v154, v138 offset:160
	ds_read_b32 v155, v138 offset:17060
	ds_read_b32 v156, v138 offset:4320
	ds_read_b32 v157, v138 offset:21220
	s_waitcnt lgkmcnt(6)
	v_mul_f32_e32 v172, v159, v161
	v_mul_f32_e32 v173, v158, v161
	v_fma_f32 v168, v158, v160, -v172
	v_fma_f32 v169, -v159, v160, -v173
	v_mul_f32_e32 v172, v159, v163
	v_mul_f32_e32 v173, v158, v163
	v_fma_f32 v170, v158, v162, -v172
	v_fma_f32 v171, -v159, v162, -v173
	s_nop 1
	v_mfma_f32_16x16x4_f32 v[144:147], v109, v168, v[144:147]
	v_mfma_f32_16x16x4_f32 v[148:151], v109, v170, v[148:151]
	v_mfma_f32_16x16x4_f32 v[144:147], v125, v169, v[144:147]
	v_mfma_f32_16x16x4_f32 v[148:151], v125, v171, v[148:151]
	ds_read_b32 v158, v137 offset:176
	ds_read_b32 v159, v137 offset:4336
	ds_read_b32 v160, v138 offset:176
	ds_read_b32 v161, v138 offset:17076
	ds_read_b32 v162, v138 offset:4336
	ds_read_b32 v163, v138 offset:21236
	s_waitcnt lgkmcnt(6)
	v_mul_f32_e32 v172, v153, v155
	v_mul_f32_e32 v173, v152, v155
	v_fma_f32 v164, v152, v154, -v172
	v_fma_f32 v165, -v153, v154, -v173
	v_mul_f32_e32 v172, v153, v157
	v_mul_f32_e32 v173, v152, v157
	v_fma_f32 v166, v152, v156, -v172
	v_fma_f32 v167, -v153, v156, -v173
	s_nop 1
	v_mfma_f32_16x16x4_f32 v[144:147], v110, v164, v[144:147]
	v_mfma_f32_16x16x4_f32 v[148:151], v110, v166, v[148:151]
	v_mfma_f32_16x16x4_f32 v[144:147], v126, v165, v[144:147]
	v_mfma_f32_16x16x4_f32 v[148:151], v126, v167, v[148:151]
	ds_read_b32 v152, v137 offset:192
	ds_read_b32 v153, v137 offset:4352
	ds_read_b32 v154, v138 offset:192
	ds_read_b32 v155, v138 offset:17092
	ds_read_b32 v156, v138 offset:4352
	ds_read_b32 v157, v138 offset:21252
	s_waitcnt lgkmcnt(6)
	v_mul_f32_e32 v172, v159, v161
	v_mul_f32_e32 v173, v158, v161
	v_fma_f32 v168, v158, v160, -v172
	v_fma_f32 v169, -v159, v160, -v173
	v_mul_f32_e32 v172, v159, v163
	v_mul_f32_e32 v173, v158, v163
	v_fma_f32 v170, v158, v162, -v172
	v_fma_f32 v171, -v159, v162, -v173
	s_nop 1
	v_mfma_f32_16x16x4_f32 v[144:147], v111, v168, v[144:147]
	v_mfma_f32_16x16x4_f32 v[148:151], v111, v170, v[148:151]
	v_mfma_f32_16x16x4_f32 v[144:147], v127, v169, v[144:147]
	v_mfma_f32_16x16x4_f32 v[148:151], v127, v171, v[148:151]
	ds_read_b32 v158, v137 offset:208
	ds_read_b32 v159, v137 offset:4368
	ds_read_b32 v160, v138 offset:208
	ds_read_b32 v161, v138 offset:17108
	ds_read_b32 v162, v138 offset:4368
	ds_read_b32 v163, v138 offset:21268
	s_waitcnt lgkmcnt(6)
	v_mul_f32_e32 v172, v153, v155
	v_mul_f32_e32 v173, v152, v155
	v_fma_f32 v164, v152, v154, -v172
	v_fma_f32 v165, -v153, v154, -v173
	v_mul_f32_e32 v172, v153, v157
	v_mul_f32_e32 v173, v152, v157
	v_fma_f32 v166, v152, v156, -v172
	v_fma_f32 v167, -v153, v156, -v173
	s_nop 1
	v_mfma_f32_16x16x4_f32 v[144:147], v112, v164, v[144:147]
	v_mfma_f32_16x16x4_f32 v[148:151], v112, v166, v[148:151]
	v_mfma_f32_16x16x4_f32 v[144:147], v128, v165, v[144:147]
	v_mfma_f32_16x16x4_f32 v[148:151], v128, v167, v[148:151]
	ds_read_b32 v152, v137 offset:224
	ds_read_b32 v153, v137 offset:4384
	ds_read_b32 v154, v138 offset:224
	ds_read_b32 v155, v138 offset:17124
	ds_read_b32 v156, v138 offset:4384
	ds_read_b32 v157, v138 offset:21284
	s_waitcnt lgkmcnt(6)
	v_mul_f32_e32 v172, v159, v161
	v_mul_f32_e32 v173, v158, v161
	v_fma_f32 v168, v158, v160, -v172
	v_fma_f32 v169, -v159, v160, -v173
	v_mul_f32_e32 v172, v159, v163
	v_mul_f32_e32 v173, v158, v163
	v_fma_f32 v170, v158, v162, -v172
	v_fma_f32 v171, -v159, v162, -v173
	s_nop 1
	v_mfma_f32_16x16x4_f32 v[144:147], v113, v168, v[144:147]
	v_mfma_f32_16x16x4_f32 v[148:151], v113, v170, v[148:151]
	v_mfma_f32_16x16x4_f32 v[144:147], v129, v169, v[144:147]
	v_mfma_f32_16x16x4_f32 v[148:151], v129, v171, v[148:151]
	ds_read_b32 v158, v137 offset:240
	ds_read_b32 v159, v137 offset:4400
	ds_read_b32 v160, v138 offset:240
	ds_read_b32 v161, v138 offset:17140
	ds_read_b32 v162, v138 offset:4400
	ds_read_b32 v163, v138 offset:21300
	s_waitcnt lgkmcnt(6)
	v_mul_f32_e32 v172, v153, v155
	v_mul_f32_e32 v173, v152, v155
	v_fma_f32 v164, v152, v154, -v172
	v_fma_f32 v165, -v153, v154, -v173
	v_mul_f32_e32 v172, v153, v157
	v_mul_f32_e32 v173, v152, v157
	v_fma_f32 v166, v152, v156, -v172
	v_fma_f32 v167, -v153, v156, -v173
	s_nop 1
	v_mfma_f32_16x16x4_f32 v[144:147], v114, v164, v[144:147]
	v_mfma_f32_16x16x4_f32 v[148:151], v114, v166, v[148:151]
	v_mfma_f32_16x16x4_f32 v[144:147], v130, v165, v[144:147]
	v_mfma_f32_16x16x4_f32 v[148:151], v130, v167, v[148:151]
	s_waitcnt lgkmcnt(0)
	v_mul_f32_e32 v172, v159, v161
	v_mul_f32_e32 v173, v158, v161
	v_fma_f32 v168, v158, v160, -v172
	v_fma_f32 v169, -v159, v160, -v173
	v_mul_f32_e32 v172, v159, v163
	v_mul_f32_e32 v173, v158, v163
	v_fma_f32 v170, v158, v162, -v172
	v_fma_f32 v171, -v159, v162, -v173
	s_nop 1
	v_mfma_f32_16x16x4_f32 v[144:147], v115, v168, v[144:147]
	v_mfma_f32_16x16x4_f32 v[148:151], v115, v170, v[148:151]
	v_mfma_f32_16x16x4_f32 v[144:147], v131, v169, v[144:147]
	v_mfma_f32_16x16x4_f32 v[148:151], v131, v171, v[148:151]
	s_nop 9
	v_cvt_pk_bf16_f32 v174, v144, v145
	v_cvt_pk_bf16_f32 v175, v146, v147
	v_cvt_pk_bf16_f32 v176, v148, v149
	v_cvt_pk_bf16_f32 v177, v150, v151
	global_store_dwordx2 v[140:141], v[174:175], off
	global_store_dwordx2 v[140:141], v[176:177], off offset:512
	v_readlane_b32 s4, v230, 7
	v_xor_b32_e32 v1, 63, v26
	v_lshlrev_b32_e32 v32, 1, v2
	v_readlane_b32 s6, v230, 9
	v_readlane_b32 s7, v230, 10
	v_mul_u32_u24_e32 v1, 0x41, v1
	s_lshl_b32 s0, s90, 7
	v_lshl_add_u64 v[2:3], s[6:7], 0, v[32:33]
	s_mov_b32 s1, 0
	v_readlane_b32 s5, v230, 8
	v_readlane_b32 s8, v230, 11
	v_readlane_b32 s9, v230, 12
	v_readlane_b32 s10, v230, 13
	v_readlane_b32 s11, v230, 14
